# idle-tail filling: phase 0 transposes only the two weights phases 2/3 need; w_in + late weights go to the phase-2 tail, ffn2 gate/up to the phase-3 ctx tail (after the moved bias rows)
# speedup vs baseline: 1.0086x; 1.0086x over previous
; __device__ __forceinline__ void phase0(const Params& P, unsigned char* smem) {
;     ...
;     auto lookup = [&](int it, TItem& t, int& N) {
;         int r = it < total ? it : total - 1;
;         t.src = nullptr; t.dst = nullptr; t.K = 0; t.mode = 0; t.n0 = 0; N = 0;
; #pragma unroll
;         for (int i = 0; i < 11; ++i) {
;             const int cnt = (tw[i].K >> 6) * (tw[i].N >> 5);
;             if (r >= 0 && r < cnt) {
;                 const int nblk = tw[i].N >> 5, kb = r / nblk, nb = r - kb * nblk, k0 = kb * 64, n0 = nb * 32, tid = threadIdx.x & 255;
;                 N = tw[i].N; t.K = tw[i].K; t.mode = tw[i].mode; t.n0 = n0;
;                 t.src = P.in[tw[i].in] + (size_t)(k0 + (tid >> 5)) * tw[i].N + n0 + (tid & 31);
;                 t.dst = (bf16_t*)(P.ws + tw[i].off) + k0 + (tid & 7) * 8;
;             }
;             r -= cnt;
;         }
;     };
.Ltr_ic:
	s_mov_b32 s1, s0
	s_mov_b32 s2, 0
	s_add_u32 s19, s1, 0x0
	s_cmpk_lt_u32 s19, 0x580
	s_cbranch_scc1 .Ltr1_m0
	s_cmpk_lt_u32 s19, 0xb00
	s_cbranch_scc1 .Ltr1_m1
	s_cmpk_lt_u32 s19, 0x1080
	s_cbranch_scc1 .Ltr1_m2
	s_cmpk_lt_u32 s19, 0x1600
	s_cbranch_scc1 .Ltr1_m3
	s_cmpk_lt_u32 s19, 0x1b80
	s_cbranch_scc1 .Ltr1_m4
	s_cmpk_lt_u32 s19, 0x2100
	s_cbranch_scc1 .Ltr1_m5
	s_cmpk_lt_u32 s19, 0x2910
	s_cbranch_scc1 .Ltr1_m6
	s_cmpk_lt_u32 s19, 0x2990
	s_cbranch_scc1 .Ltr1_m7
	s_cmpk_lt_u32 s19, 0x2a90
	s_cbranch_scc1 .Ltr1_m8
	s_cmpk_lt_u32 s19, 0x2b90
	s_cbranch_scc1 .Ltr1_m9
	s_sub_u32 s3, s19, 0x2b90
	v_readlane_b32 s6, v251, 43
	v_readlane_b32 s7, v251, 44
	s_mov_b32 s13, 0x2c00000
	s_mov_b32 s14, 0
	s_branch .Ltr1_c1024_1024

; __device__ __forceinline__ void phase0(const Params& P, unsigned char* smem) {
;     ...
;         for (int base = blockIdx.x * 2; base < total; base += stride) {
;             float v[8];
; #pragma unroll
;             for (int i = 0; i < 8; ++i) v[i] = vn[i];
;             cur = nxt; Nc = Nn;
;             if (base + stride < total) { lookup(it + stride, nxt, Nn); transpose_load(nxt, Nn, vn); }
;             transpose_store(cur, v, scr);
;             it += stride;
;         }
.Ltr_le1:
	s_add_u32 s2, s2, 1
	s_cmp_lt_u32 s2, 2
	s_cbranch_scc1 .Ltr2_common
	s_cmp_lg_u32 s17, 0
	s_cbranch_scc1 .Ltr_last0f
	s_cmp_eq_u32 s2, 2
	s_cbranch_scc0 .Ltr2_stride
	s_add_u32 s1, s18, 0x1000
	s_branch .Ltr2_chk

; __device__ __forceinline__ void phase0(const Params& P, unsigned char* smem) {
;     ...
;     auto lookup = [&](int it, TItem& t, int& N) {
;         int r = it < total ? it : total - 1;
;         t.src = nullptr; t.dst = nullptr; t.K = 0; t.mode = 0; t.n0 = 0; N = 0;
; #pragma unroll
;         for (int i = 0; i < 11; ++i) {
;             const int cnt = (tw[i].K >> 6) * (tw[i].N >> 5);
;             if (r >= 0 && r < cnt) {
;                 const int nblk = tw[i].N >> 5, kb = r / nblk, nb = r - kb * nblk, k0 = kb * 64, n0 = nb * 32, tid = threadIdx.x & 255;
;                 N = tw[i].N; t.K = tw[i].K; t.mode = tw[i].mode; t.n0 = n0;
;                 t.src = P.in[tw[i].in] + (size_t)(k0 + (tid >> 5)) * tw[i].N + n0 + (tid & 31);
;                 t.dst = (bf16_t*)(P.ws + tw[i].off) + k0 + (tid & 7) * 8;
;             }
;             r -= cnt;
;         }
;     };
.Ltr2_chk:
	s_cmpk_lt_u32 s1, 0x1080
	s_cbranch_scc0 .Ltr_last0f
	s_add_u32 s19, s1, 0x0
	s_cmpk_lt_u32 s19, 0x580
	s_cbranch_scc1 .Ltr3_m0
	s_cmpk_lt_u32 s19, 0xb00
	s_cbranch_scc1 .Ltr3_m1
	s_cmpk_lt_u32 s19, 0x1080
	s_cbranch_scc1 .Ltr3_m2
	s_cmpk_lt_u32 s19, 0x1600
	s_cbranch_scc1 .Ltr3_m3
	s_cmpk_lt_u32 s19, 0x1b80
	s_cbranch_scc1 .Ltr3_m4
	s_cmpk_lt_u32 s19, 0x2100
	s_cbranch_scc1 .Ltr3_m5
	s_cmpk_lt_u32 s19, 0x2910
	s_cbranch_scc1 .Ltr3_m6
	s_cmpk_lt_u32 s19, 0x2990
	s_cbranch_scc1 .Ltr3_m7
	s_cmpk_lt_u32 s19, 0x2a90
	s_cbranch_scc1 .Ltr3_m8
	s_cmpk_lt_u32 s19, 0x2b90
	s_cbranch_scc1 .Ltr3_m9
	s_sub_u32 s3, s19, 0x2b90
	v_readlane_b32 s6, v251, 43
	v_readlane_b32 s7, v251, 44
	s_mov_b32 s13, 0x2c00000
	s_mov_b32 s14, 0
	s_branch .Ltr3_c1024_1024

; __device__ __forceinline__ void phase0(const Params& P, unsigned char* smem) {
;     ...
;         for (int base = blockIdx.x * 2; base < total; base += stride) {
;             float v[8];
; #pragma unroll
;             for (int i = 0; i < 8; ++i) v[i] = vn[i];
;             cur = nxt; Nc = Nn;
;             if (base + stride < total) { lookup(it + stride, nxt, Nn); transpose_load(nxt, Nn, vn); }
;             transpose_store(cur, v, scr);
;             it += stride;
;         }
.Ltr_pe1:
.Ltr_loop:
	s_add_u32 s2, s2, 1
	s_cmp_lt_u32 s2, 2
	s_cbranch_scc1 .Ltr4_common
	s_cmp_lg_u32 s17, 0
	s_cbranch_scc1 .Ltr_last1
	s_cmp_eq_u32 s2, 2
	s_cbranch_scc0 .Ltr4_stride
	s_add_u32 s1, s18, 0x1000
	s_branch .Ltr4_chk

; __device__ __forceinline__ void phase0(const Params& P, unsigned char* smem) {
;     ...
;     const int gtid = blockIdx.x * NTHR + threadIdx.x, gsz = gridDim.x * NTHR;
;     for (int e = gtid; e < NT + 2 * NL; e += gsz) ((float*)(P.ws + OFF_SS))[e] = 0.f;
.Ltr_pe5:
.Ltr_done:
	v_readlane_b32 s0, v251, 1
	v_readlane_b32 s1, v251, 2
	s_nop 3
	s_load_dword s2, s[0:1], 0x10
	s_waitcnt lgkmcnt(0)
	s_lshr_b32 s0, s2, 16
	s_and_b32 s0, 0xffff, s0
	s_cmp_lg_u32 s0, 0
	s_cselect_b64 s[0:1], -1, 0
	s_cmp_lg_u64 s[0:1], 0
	s_addc_u32 s30, s90, 0
	s_branch .Ltr_pad
	s_nop 0
.Ltr_pad:
.LBB0_94:
	v_lshl_add_u32 v2, s33, 9, v168
	s_mov_b32 s0, 0x18400
	s_lshl_b32 s52, s30, 9
	v_cmp_gt_i32_e32 vcc, s0, v2
	s_and_saveexec_b64 s[2:3], vcc
	s_cbranch_execz .LBB0_102
	v_cvt_f32_u32_e32 v1, s52
	v_add_u32_e32 v3, s52, v2
	v_mov_b32_e32 v4, s52
	v_cmp_gt_i32_e32 vcc, s0, v3
	v_rcp_iflag_f32_e32 v1, v1
	s_sub_i32 s4, 0, s52
	v_max_i32_e32 v5, 0x18400, v3
	v_addc_co_u32_e64 v4, s[0:1], v2, v4, vcc
	v_mul_f32_e32 v1, 0x4f7ffffe, v1
	v_cvt_u32_f32_e32 v1, v1
	v_sub_u32_e32 v4, v5, v4
	v_mul_lo_u32 v5, s4, v1
	v_mul_hi_u32 v5, v1, v5
	v_add_u32_e32 v1, v1, v5
	v_mul_hi_u32 v1, v4, v1
	v_mul_lo_u32 v5, v1, s52
	v_sub_u32_e32 v4, v4, v5
	v_add_u32_e32 v6, 1, v1
	v_cmp_le_u32_e64 s[0:1], s52, v4
	v_subrev_u32_e32 v5, s52, v4
	s_mov_b64 s[4:5], -1
	v_cndmask_b32_e64 v1, v1, v6, s[0:1]
	v_cndmask_b32_e64 v4, v4, v5, s[0:1]
	v_add_u32_e32 v5, 1, v1
	v_cmp_le_u32_e64 s[0:1], s52, v4
	v_mov_b32_e32 v4, v2
	s_nop 0
	v_cndmask_b32_e64 v1, v1, v5, s[0:1]
	v_addc_co_u32_e32 v1, vcc, 1, v1, vcc
	v_cmp_lt_u32_e32 vcc, 1, v1
	s_and_saveexec_b64 s[0:1], vcc
	s_cbranch_execz .LBB0_99
	s_add_u32 s4, s68, 0x1ef41000
	s_addc_u32 s5, s69, 0
	v_and_b32_e32 v6, -2, v1
	s_lshl_b32 s7, s30, 10
	s_mov_b32 s20, s7
	s_mov_b64 s[10:11], 0
	v_mov_b32_e32 v7, 0
	v_mov_b32_e32 v8, v6
	v_mov_b64_e32 v[4:5], v[2:3]

; __device__ __forceinline__ void phase0(const Params& P, unsigned char* smem) {
;     ...
;     auto lookup = [&](int it, TItem& t, int& N) {
;         int r = it < total ? it : total - 1;
;         t.src = nullptr; t.dst = nullptr; t.K = 0; t.mode = 0; t.n0 = 0; N = 0;
; #pragma unroll
;         for (int i = 0; i < 11; ++i) {
;             const int cnt = (tw[i].K >> 6) * (tw[i].N >> 5);
;             if (r >= 0 && r < cnt) {
;                 const int nblk = tw[i].N >> 5, kb = r / nblk, nb = r - kb * nblk, k0 = kb * 64, n0 = nb * 32, tid = threadIdx.x & 255;
;                 N = tw[i].N; t.K = tw[i].K; t.mode = tw[i].mode; t.n0 = n0;
;                 t.src = P.in[tw[i].in] + (size_t)(k0 + (tid >> 5)) * tw[i].N + n0 + (tid & 31);
;                 t.dst = (bf16_t*)(P.ws + tw[i].off) + k0 + (tid & 7) * 8;
;             }
;             r -= cnt;
;         }
;     };
;     {
;         const int stride = gridDim.x * 2;
;         int it = blockIdx.x * 2 + hb;
;         TItem cur, nxt; int Nc = 0, Nn = 0; float vn[8];
;         if (blockIdx.x * 2 < total) { lookup(it, nxt, Nn); transpose_load(nxt, Nn, vn); }
;         for (int base = blockIdx.x * 2; base < total; base += stride) {
;             float v[8];
; #pragma unroll
;             for (int i = 0; i < 8; ++i) v[i] = vn[i];
;             cur = nxt; Nc = Nn;
;             if (base + stride < total) { lookup(it + stride, nxt, Nn); transpose_load(nxt, Nn, vn); }
;             transpose_store(cur, v, scr);
;             it += stride;
;         }
;     }
.LBB0_282:
	s_cmpk_lt_u32 s33, 0x58
	s_cbranch_scc1 .Ltq_skip
	v_and_b32_e32 v1, 63, v168
	v_lshrrev_b32_e32 v14, 6, v168
	s_nop 1
	v_readfirstlane_b32 s0, v14
	s_nop 3
	v_lshrrev_b32_e32 v2, 3, v1
	v_and_b32_e32 v3, 7, v1
	v_lshrrev_b32_e32 v4, 2, v2
	v_and_b32_e32 v14, 3, v2
	v_lshl_or_b32 v4, v4, 3, v14
	s_mulk_i32 s0, 0x2100
	s_add_u32 s3, s0, 16
	v_mul_u32_u24_e32 v5, 0x84, v2
	v_lshl_add_u32 v5, v3, 4, v5
	v_add_u32_e32 v5, s3, v5
	v_add_u32_e32 v6, 0x420, v5
	v_add_u32_e32 v7, 0x420, v6
	v_add_u32_e32 v8, 0x420, v7
	v_add_u32_e32 v9, 0x420, v8
	v_add_u32_e32 v10, 0x420, v9
	v_add_u32_e32 v11, 0x420, v10
	v_add_u32_e32 v12, 0x420, v11
	v_mul_u32_u24_e32 v13, 0x420, v3
	v_lshl_add_u32 v13, v2, 2, v13
	v_add_u32_e32 v13, s3, v13
	v_lshlrev_b32_e32 v3, 4, v3
	v_lshrrev_b32_e32 v14, 6, v168
	s_nop 1
	v_readfirstlane_b32 s0, v14
	s_nop 3
	s_sub_u32 s4, s33, 88
	s_lshl_b32 s4, s4, 3
	s_add_u32 s0, s0, s4
	s_mov_b32 s1, s0
	s_add_u32 s19, s1, 0x1b80
	s_cmpk_lt_u32 s19, 0x580
	s_cbranch_scc1 .Ltq1_m0
	s_cmpk_lt_u32 s19, 0xb00
	s_cbranch_scc1 .Ltq1_m1
	s_cmpk_lt_u32 s19, 0x1080
	s_cbranch_scc1 .Ltq1_m2
	s_cmpk_lt_u32 s19, 0x1600
	s_cbranch_scc1 .Ltq1_m3
	s_cmpk_lt_u32 s19, 0x1b80
	s_cbranch_scc1 .Ltq1_m4
	s_cmpk_lt_u32 s19, 0x2100
	s_cbranch_scc1 .Ltq1_m5
	s_cmpk_lt_u32 s19, 0x2910
	s_cbranch_scc1 .Ltq1_m6
	s_cmpk_lt_u32 s19, 0x2990
	s_cbranch_scc1 .Ltq1_m7
	s_cmpk_lt_u32 s19, 0x2a90
	s_cbranch_scc1 .Ltq1_m8
	s_cmpk_lt_u32 s19, 0x2b90
	s_cbranch_scc1 .Ltq1_m9
	s_sub_u32 s3, s19, 0x2b90
	v_readlane_b32 s6, v251, 43
	v_readlane_b32 s7, v251, 44
	s_mov_b32 s13, 0x2c00000
	s_mov_b32 s14, 0
	s_branch .Ltq1_c1024_1024

; __device__ __forceinline__ void phase0(const Params& P, unsigned char* smem) {
;     ...
;     auto lookup = [&](int it, TItem& t, int& N) {
;         int r = it < total ? it : total - 1;
;         t.src = nullptr; t.dst = nullptr; t.K = 0; t.mode = 0; t.n0 = 0; N = 0;
; #pragma unroll
;         for (int i = 0; i < 11; ++i) {
;             const int cnt = (tw[i].K >> 6) * (tw[i].N >> 5);
;             if (r >= 0 && r < cnt) {
;                 const int nblk = tw[i].N >> 5, kb = r / nblk, nb = r - kb * nblk, k0 = kb * 64, n0 = nb * 32, tid = threadIdx.x & 255;
;                 N = tw[i].N; t.K = tw[i].K; t.mode = tw[i].mode; t.n0 = n0;
;                 t.src = P.in[tw[i].in] + (size_t)(k0 + (tid >> 5)) * tw[i].N + n0 + (tid & 31);
;                 t.dst = (bf16_t*)(P.ws + tw[i].off) + k0 + (tid & 7) * 8;
;             }
;             r -= cnt;
;         }
;     };
;     {
;         const int stride = gridDim.x * 2;
;         int it = blockIdx.x * 2 + hb;
;         TItem cur, nxt; int Nc = 0, Nn = 0; float vn[8];
;         if (blockIdx.x * 2 < total) { lookup(it, nxt, Nn); transpose_load(nxt, Nn, vn); }
;         for (int base = blockIdx.x * 2; base < total; base += stride) {
;             float v[8];
; #pragma unroll
;             for (int i = 0; i < 8; ++i) v[i] = vn[i];
;             cur = nxt; Nc = Nn;
;             if (base + stride < total) { lookup(it + stride, nxt, Nn); transpose_load(nxt, Nn, vn); }
;             transpose_store(cur, v, scr);
;             it += stride;
;         }
.Ltq_le1:
	s_add_u32 s1, s1, 0x540
	s_cmpk_lt_u32 s1, 0x1210
	s_cbranch_scc0 .Ltq_last0f
	s_add_u32 s19, s1, 0x1b80
	s_cmpk_lt_u32 s19, 0x580
	s_cbranch_scc1 .Ltq2_m0
	s_cmpk_lt_u32 s19, 0xb00
	s_cbranch_scc1 .Ltq2_m1
	s_cmpk_lt_u32 s19, 0x1080
	s_cbranch_scc1 .Ltq2_m2
	s_cmpk_lt_u32 s19, 0x1600
	s_cbranch_scc1 .Ltq2_m3
	s_cmpk_lt_u32 s19, 0x1b80
	s_cbranch_scc1 .Ltq2_m4
	s_cmpk_lt_u32 s19, 0x2100
	s_cbranch_scc1 .Ltq2_m5
	s_cmpk_lt_u32 s19, 0x2910
	s_cbranch_scc1 .Ltq2_m6
	s_cmpk_lt_u32 s19, 0x2990
	s_cbranch_scc1 .Ltq2_m7
	s_cmpk_lt_u32 s19, 0x2a90
	s_cbranch_scc1 .Ltq2_m8
	s_cmpk_lt_u32 s19, 0x2b90
	s_cbranch_scc1 .Ltq2_m9
	s_sub_u32 s3, s19, 0x2b90
	v_readlane_b32 s6, v251, 43
	v_readlane_b32 s7, v251, 44
	s_mov_b32 s13, 0x2c00000
	s_mov_b32 s14, 0
	s_branch .Ltq2_c1024_1024

; __device__ __forceinline__ void phase0(const Params& P, unsigned char* smem) {
;     ...
;     auto lookup = [&](int it, TItem& t, int& N) {
;         int r = it < total ? it : total - 1;
;         t.src = nullptr; t.dst = nullptr; t.K = 0; t.mode = 0; t.n0 = 0; N = 0;
; #pragma unroll
;         for (int i = 0; i < 11; ++i) {
;             const int cnt = (tw[i].K >> 6) * (tw[i].N >> 5);
;             if (r >= 0 && r < cnt) {
;                 const int nblk = tw[i].N >> 5, kb = r / nblk, nb = r - kb * nblk, k0 = kb * 64, n0 = nb * 32, tid = threadIdx.x & 255;
;                 N = tw[i].N; t.K = tw[i].K; t.mode = tw[i].mode; t.n0 = n0;
;                 t.src = P.in[tw[i].in] + (size_t)(k0 + (tid >> 5)) * tw[i].N + n0 + (tid & 31);
;                 t.dst = (bf16_t*)(P.ws + tw[i].off) + k0 + (tid & 7) * 8;
;             }
;             r -= cnt;
;         }
;     };
;     {
;         const int stride = gridDim.x * 2;
;         int it = blockIdx.x * 2 + hb;
;         TItem cur, nxt; int Nc = 0, Nn = 0; float vn[8];
;         if (blockIdx.x * 2 < total) { lookup(it, nxt, Nn); transpose_load(nxt, Nn, vn); }
;         for (int base = blockIdx.x * 2; base < total; base += stride) {
;             float v[8];
; #pragma unroll
;             for (int i = 0; i < 8; ++i) v[i] = vn[i];
;             cur = nxt; Nc = Nn;
;             if (base + stride < total) { lookup(it + stride, nxt, Nn); transpose_load(nxt, Nn, vn); }
;             transpose_store(cur, v, scr);
;             it += stride;
;         }
.Ltq_pe1:
.Ltq_loop:
	s_add_u32 s1, s1, 0x540
	s_cmpk_lt_u32 s1, 0x1210
	s_cbranch_scc0 .Ltq_last1
	s_add_u32 s19, s1, 0x1b80
	s_cmpk_lt_u32 s19, 0x580
	s_cbranch_scc1 .Ltq3_m0
	s_cmpk_lt_u32 s19, 0xb00
	s_cbranch_scc1 .Ltq3_m1
	s_cmpk_lt_u32 s19, 0x1080
	s_cbranch_scc1 .Ltq3_m2
	s_cmpk_lt_u32 s19, 0x1600
	s_cbranch_scc1 .Ltq3_m3
	s_cmpk_lt_u32 s19, 0x1b80
	s_cbranch_scc1 .Ltq3_m4
	s_cmpk_lt_u32 s19, 0x2100
	s_cbranch_scc1 .Ltq3_m5
	s_cmpk_lt_u32 s19, 0x2910
	s_cbranch_scc1 .Ltq3_m6
	s_cmpk_lt_u32 s19, 0x2990
	s_cbranch_scc1 .Ltq3_m7
	s_cmpk_lt_u32 s19, 0x2a90
	s_cbranch_scc1 .Ltq3_m8
	s_cmpk_lt_u32 s19, 0x2b90
	s_cbranch_scc1 .Ltq3_m9
	s_sub_u32 s3, s19, 0x2b90
	v_readlane_b32 s6, v251, 43
	v_readlane_b32 s7, v251, 44
	s_mov_b32 s13, 0x2c00000
	s_mov_b32 s14, 0
	s_branch .Ltq3_c1024_1024

; __device__ __forceinline__ void phase4(const Params& P) {
;     ...
;     auto kf_val = [&](int e) -> float {
;         const int k = e & 511, n = (e >> 9) & 511, g = e >> 18;
;         const int t = n >> 4, c = n & 15, s = k >> 4, cp = k & 15;
;         const int d0 = t - s, d1 = s - t;
;         const float a0 = KD[(((0 * 32 + g) * 32 + (d0 > 0 ? d0 : 0)) * 16 + c) * 16 + cp];
;         const float a1 = KD[(((1 * 32 + g) * 32 + (d1 > 0 ? d1 : 0)) * 16 + c) * 16 + cp];
.Ltq_pe5:
.Ltq_done:
	s_nop 0
	s_nop 0
	s_nop 0
	s_nop 0
	s_nop 0
	s_nop 0
	s_nop 0
	s_nop 0
	s_nop 0
	s_nop 0
	s_nop 0
	v_lshrrev_b32_e32 v0, 1, v170
	v_and_b32_e32 v1, 1, v170
	v_lshlrev_b32_e32 v2, 4, v170
	v_lshlrev_b32_e32 v1, 5, v1
	v_readfirstlane_b32 s0, v171
	s_nop 3
	s_sub_u32 s1, s33, 88
	s_lshl_b32 s1, s1, 3
	s_add_u32 s0, s0, s1

; __device__ __forceinline__ void xcd_barrier(const XcdBarrier& b) {
;     asm volatile("s_waitcnt vmcnt(0)" ::: "memory");
;     __syncthreads();
;     if (threadIdx.x == 0) {
;         unsigned* bar = b.bar;
;         __builtin_amdgcn_s_waitcnt(0);
;         unsigned nloc = b.st[0], nx = b.st[1];
;         if (nloc == 0u) { xcd_barrier_complete(bar, b.x, nloc, nx); b.st[0] = nloc; b.st[1] = nx; }
.Lkt_done:
.Ltq_skip:
	s_cmp_lt_i32 s71, 4
	s_cbranch_scc1 .LBB0_332
	s_waitcnt vmcnt(0)
	s_waitcnt vmcnt(0) lgkmcnt(0)
	s_barrier
	s_mov_b64 s[0:1], exec
	v_readlane_b32 s2, v251, 3
	v_readlane_b32 s3, v251, 4
	s_and_b64 s[2:3], s[0:1], s[2:3]
	s_mov_b64 exec, s[2:3]
	s_cbranch_execz .LBB0_331
	v_mov_b32_e32 v0, 0
	s_waitcnt vmcnt(0) expcnt(0) lgkmcnt(0)
	ds_read_b32 v2, v0
	ds_read_b32 v1, v0 offset:4
	s_waitcnt lgkmcnt(1)
	v_cmp_ne_u32_e32 vcc, 0, v2
	s_cbranch_vccnz .LBB0_299
	v_readlane_b32 s2, v251, 0
	s_mul_i32 s48, s91, s2
	s_add_u32 s2, s68, 0x1ef3d200
	s_addc_u32 s3, s69, 0
	s_add_u32 s4, s68, 0x1ef3d400
	s_addc_u32 s5, s69, 0
	s_add_u32 s6, s68, 0x1ef3d500
	s_addc_u32 s7, s69, 0
	s_add_u32 s10, s68, 0x1ef3d600
	s_addc_u32 s11, s69, 0
	s_add_u32 s12, s68, 0x1ef3d700
	s_addc_u32 s13, s69, 0
	s_add_u32 s14, s68, 0x1ef3d800
	s_addc_u32 s15, s69, 0
	s_add_u32 s16, s68, 0x1ef3d900
	s_addc_u32 s17, s69, 0
	s_add_u32 s18, s68, 0x1ef3da00
	s_addc_u32 s19, s69, 0
	s_add_u32 s20, s68, 0x1ef3db00
	s_addc_u32 s21, s69, 0
	s_add_u32 s22, s68, 0x1ef3dc00
	s_addc_u32 s23, s69, 0
	s_add_u32 s24, s68, 0x1ef3dd00
	s_addc_u32 s25, s69, 0
	s_add_u32 s26, s68, 0x1ef3de00
	s_addc_u32 s27, s69, 0
	s_add_u32 s28, s68, 0x1ef3df00
	s_addc_u32 s29, s69, 0
	s_add_u32 s30, s68, 0x1ef3e000
	s_addc_u32 s31, s69, 0
	s_add_u32 s34, s68, 0x1ef3e100
	s_addc_u32 s35, s69, 0
	s_add_u32 s38, s68, 0x1ef3e200
	s_addc_u32 s39, s69, 0
	s_add_u32 s40, s68, 0x1ef3e300
	s_mul_i32 s48, s48, s90
	s_addc_u32 s41, s69, 0
	s_mov_b32 s49, 1
	s_branch .LBB0_287

; __device__ __forceinline__ void phase0(const Params& P, unsigned char* smem) {
;     ...
;     auto lookup = [&](int it, TItem& t, int& N) {
;         int r = it < total ? it : total - 1;
;         t.src = nullptr; t.dst = nullptr; t.K = 0; t.mode = 0; t.n0 = 0; N = 0;
; #pragma unroll
;         for (int i = 0; i < 11; ++i) {
;             const int cnt = (tw[i].K >> 6) * (tw[i].N >> 5);
;             if (r >= 0 && r < cnt) {
;                 const int nblk = tw[i].N >> 5, kb = r / nblk, nb = r - kb * nblk, k0 = kb * 64, n0 = nb * 32, tid = threadIdx.x & 255;
;                 N = tw[i].N; t.K = tw[i].K; t.mode = tw[i].mode; t.n0 = n0;
;                 t.src = P.in[tw[i].in] + (size_t)(k0 + (tid >> 5)) * tw[i].N + n0 + (tid & 31);
;                 t.dst = (bf16_t*)(P.ws + tw[i].off) + k0 + (tid & 7) * 8;
;             }
;             r -= cnt;
;         }
;     };
;     {
;         const int stride = gridDim.x * 2;
;         int it = blockIdx.x * 2 + hb;
;         TItem cur, nxt; int Nc = 0, Nn = 0; float vn[8];
;         if (blockIdx.x * 2 < total) { lookup(it, nxt, Nn); transpose_load(nxt, Nn, vn); }
;         for (int base = blockIdx.x * 2; base < total; base += stride) {
;             float v[8];
; #pragma unroll
;             for (int i = 0; i < 8; ++i) v[i] = vn[i];
;             cur = nxt; Nc = Nn;
;             if (base + stride < total) { lookup(it + stride, nxt, Nn); transpose_load(nxt, Nn, vn); }
;             transpose_store(cur, v, scr);
;             it += stride;
;         }
;     }
.Lbwa_end:
	s_mov_b64 exec, -1
	v_and_b32_e32 v1, 63, v168
	v_lshrrev_b32_e32 v14, 6, v168
	s_nop 1
	v_readfirstlane_b32 s0, v14
	s_nop 3
	v_lshrrev_b32_e32 v2, 3, v1
	v_and_b32_e32 v3, 7, v1
	v_lshrrev_b32_e32 v4, 2, v2
	v_and_b32_e32 v14, 3, v2
	v_lshl_or_b32 v4, v4, 3, v14
	s_mulk_i32 s0, 0x2100
	s_add_u32 s3, s0, 16
	v_mul_u32_u24_e32 v5, 0x84, v2
	v_lshl_add_u32 v5, v3, 4, v5
	v_add_u32_e32 v5, s3, v5
	v_add_u32_e32 v6, 0x420, v5
	v_add_u32_e32 v7, 0x420, v6
	v_add_u32_e32 v8, 0x420, v7
	v_add_u32_e32 v9, 0x420, v8
	v_add_u32_e32 v10, 0x420, v9
	v_add_u32_e32 v11, 0x420, v10
	v_add_u32_e32 v12, 0x420, v11
	v_mul_u32_u24_e32 v13, 0x420, v3
	v_lshl_add_u32 v13, v2, 2, v13
	v_add_u32_e32 v13, s3, v13
	v_lshlrev_b32_e32 v3, 4, v3
	v_lshrrev_b32_e32 v14, 6, v168
	s_nop 1
	v_readfirstlane_b32 s0, v14
	s_nop 3
	s_sub_u32 s4, s33, 176
	s_lshl_b32 s4, s4, 3
	s_add_u32 s0, s0, s4
	s_mov_b32 s1, s0
	s_add_u32 s19, s1, 0x1080
	s_cmpk_lt_u32 s19, 0x580
	s_cbranch_scc1 .Ltp1_m0
	s_cmpk_lt_u32 s19, 0xb00
	s_cbranch_scc1 .Ltp1_m1
	s_cmpk_lt_u32 s19, 0x1080
	s_cbranch_scc1 .Ltp1_m2
	s_cmpk_lt_u32 s19, 0x1600
	s_cbranch_scc1 .Ltp1_m3
	s_cmpk_lt_u32 s19, 0x1b80
	s_cbranch_scc1 .Ltp1_m4
	s_cmpk_lt_u32 s19, 0x2100
	s_cbranch_scc1 .Ltp1_m5
	s_cmpk_lt_u32 s19, 0x2910
	s_cbranch_scc1 .Ltp1_m6
	s_cmpk_lt_u32 s19, 0x2990
	s_cbranch_scc1 .Ltp1_m7
	s_cmpk_lt_u32 s19, 0x2a90
	s_cbranch_scc1 .Ltp1_m8
	s_cmpk_lt_u32 s19, 0x2b90
	s_cbranch_scc1 .Ltp1_m9
	s_sub_u32 s3, s19, 0x2b90
	v_readlane_b32 s6, v251, 43
	v_readlane_b32 s7, v251, 44
	s_mov_b32 s13, 0x2c00000
	s_mov_b32 s14, 0
	s_branch .Ltp1_c1024_1024

; __device__ __forceinline__ void phase0(const Params& P, unsigned char* smem) {
;     ...
;     auto lookup = [&](int it, TItem& t, int& N) {
;         int r = it < total ? it : total - 1;
;         t.src = nullptr; t.dst = nullptr; t.K = 0; t.mode = 0; t.n0 = 0; N = 0;
; #pragma unroll
;         for (int i = 0; i < 11; ++i) {
;             const int cnt = (tw[i].K >> 6) * (tw[i].N >> 5);
;             if (r >= 0 && r < cnt) {
;                 const int nblk = tw[i].N >> 5, kb = r / nblk, nb = r - kb * nblk, k0 = kb * 64, n0 = nb * 32, tid = threadIdx.x & 255;
;                 N = tw[i].N; t.K = tw[i].K; t.mode = tw[i].mode; t.n0 = n0;
;                 t.src = P.in[tw[i].in] + (size_t)(k0 + (tid >> 5)) * tw[i].N + n0 + (tid & 31);
;                 t.dst = (bf16_t*)(P.ws + tw[i].off) + k0 + (tid & 7) * 8;
;             }
;             r -= cnt;
;         }
;     };
;     {
;         const int stride = gridDim.x * 2;
;         int it = blockIdx.x * 2 + hb;
;         TItem cur, nxt; int Nc = 0, Nn = 0; float vn[8];
;         if (blockIdx.x * 2 < total) { lookup(it, nxt, Nn); transpose_load(nxt, Nn, vn); }
;         for (int base = blockIdx.x * 2; base < total; base += stride) {
;             float v[8];
; #pragma unroll
;             for (int i = 0; i < 8; ++i) v[i] = vn[i];
;             cur = nxt; Nc = Nn;
;             if (base + stride < total) { lookup(it + stride, nxt, Nn); transpose_load(nxt, Nn, vn); }
;             transpose_store(cur, v, scr);
;             it += stride;
;         }
.Ltp_le1:
	s_add_u32 s1, s1, 0x280
	s_cmpk_lt_u32 s1, 0xb00
	s_cbranch_scc0 .Ltp_last0f
	s_add_u32 s19, s1, 0x1080
	s_cmpk_lt_u32 s19, 0x580
	s_cbranch_scc1 .Ltp2_m0
	s_cmpk_lt_u32 s19, 0xb00
	s_cbranch_scc1 .Ltp2_m1
	s_cmpk_lt_u32 s19, 0x1080
	s_cbranch_scc1 .Ltp2_m2
	s_cmpk_lt_u32 s19, 0x1600
	s_cbranch_scc1 .Ltp2_m3
	s_cmpk_lt_u32 s19, 0x1b80
	s_cbranch_scc1 .Ltp2_m4
	s_cmpk_lt_u32 s19, 0x2100
	s_cbranch_scc1 .Ltp2_m5
	s_cmpk_lt_u32 s19, 0x2910
	s_cbranch_scc1 .Ltp2_m6
	s_cmpk_lt_u32 s19, 0x2990
	s_cbranch_scc1 .Ltp2_m7
	s_cmpk_lt_u32 s19, 0x2a90
	s_cbranch_scc1 .Ltp2_m8
	s_cmpk_lt_u32 s19, 0x2b90
	s_cbranch_scc1 .Ltp2_m9
	s_sub_u32 s3, s19, 0x2b90
	v_readlane_b32 s6, v251, 43
	v_readlane_b32 s7, v251, 44
	s_mov_b32 s13, 0x2c00000
	s_mov_b32 s14, 0
	s_branch .Ltp2_c1024_1024

; __device__ __forceinline__ void phase0(const Params& P, unsigned char* smem) {
;     ...
;     auto lookup = [&](int it, TItem& t, int& N) {
;         int r = it < total ? it : total - 1;
;         t.src = nullptr; t.dst = nullptr; t.K = 0; t.mode = 0; t.n0 = 0; N = 0;
; #pragma unroll
;         for (int i = 0; i < 11; ++i) {
;             const int cnt = (tw[i].K >> 6) * (tw[i].N >> 5);
;             if (r >= 0 && r < cnt) {
;                 const int nblk = tw[i].N >> 5, kb = r / nblk, nb = r - kb * nblk, k0 = kb * 64, n0 = nb * 32, tid = threadIdx.x & 255;
;                 N = tw[i].N; t.K = tw[i].K; t.mode = tw[i].mode; t.n0 = n0;
;                 t.src = P.in[tw[i].in] + (size_t)(k0 + (tid >> 5)) * tw[i].N + n0 + (tid & 31);
;                 t.dst = (bf16_t*)(P.ws + tw[i].off) + k0 + (tid & 7) * 8;
;             }
;             r -= cnt;
;         }
;     };
;     {
;         const int stride = gridDim.x * 2;
;         int it = blockIdx.x * 2 + hb;
;         TItem cur, nxt; int Nc = 0, Nn = 0; float vn[8];
;         if (blockIdx.x * 2 < total) { lookup(it, nxt, Nn); transpose_load(nxt, Nn, vn); }
;         for (int base = blockIdx.x * 2; base < total; base += stride) {
;             float v[8];
; #pragma unroll
;             for (int i = 0; i < 8; ++i) v[i] = vn[i];
;             cur = nxt; Nc = Nn;
;             if (base + stride < total) { lookup(it + stride, nxt, Nn); transpose_load(nxt, Nn, vn); }
;             transpose_store(cur, v, scr);
;             it += stride;
;         }
.Ltp_pe1:
.Ltp_loop:
	s_add_u32 s1, s1, 0x280
	s_cmpk_lt_u32 s1, 0xb00
	s_cbranch_scc0 .Ltp_last1
	s_add_u32 s19, s1, 0x1080
	s_cmpk_lt_u32 s19, 0x580
	s_cbranch_scc1 .Ltp3_m0
	s_cmpk_lt_u32 s19, 0xb00
	s_cbranch_scc1 .Ltp3_m1
	s_cmpk_lt_u32 s19, 0x1080
	s_cbranch_scc1 .Ltp3_m2
	s_cmpk_lt_u32 s19, 0x1600
	s_cbranch_scc1 .Ltp3_m3
	s_cmpk_lt_u32 s19, 0x1b80
	s_cbranch_scc1 .Ltp3_m4
	s_cmpk_lt_u32 s19, 0x2100
	s_cbranch_scc1 .Ltp3_m5
	s_cmpk_lt_u32 s19, 0x2910
	s_cbranch_scc1 .Ltp3_m6
	s_cmpk_lt_u32 s19, 0x2990
	s_cbranch_scc1 .Ltp3_m7
	s_cmpk_lt_u32 s19, 0x2a90
	s_cbranch_scc1 .Ltp3_m8
	s_cmpk_lt_u32 s19, 0x2b90
	s_cbranch_scc1 .Ltp3_m9
	s_sub_u32 s3, s19, 0x2b90
	v_readlane_b32 s6, v251, 43
	v_readlane_b32 s7, v251, 44
	s_mov_b32 s13, 0x2c00000
	s_mov_b32 s14, 0
	s_branch .Ltp3_c1024_1024

; __device__ __forceinline__ void xcd_barrier(const XcdBarrier& b) {
;     asm volatile("s_waitcnt vmcnt(0)" ::: "memory");
;     __syncthreads();
;     if (threadIdx.x == 0) {
;         unsigned* bar = b.bar;
;         __builtin_amdgcn_s_waitcnt(0);
;         unsigned nloc = b.st[0], nx = b.st[1];
;         if (nloc == 0u) { xcd_barrier_complete(bar, b.x, nloc, nx); b.st[0] = nloc; b.st[1] = nx; }
.Ltp_skip:
.LBB0_381:
	s_cmp_lt_i32 s71, 5
	s_cbranch_scc1 .LBB0_431
	s_waitcnt vmcnt(0)
	s_waitcnt vmcnt(0) lgkmcnt(0)
	s_barrier
	s_mov_b64 s[0:1], exec
	v_readlane_b32 s2, v251, 3
	v_readlane_b32 s3, v251, 4
	s_and_b64 s[2:3], s[0:1], s[2:3]
	s_mov_b64 exec, s[2:3]
	s_cbranch_execz .LBB0_430
	v_mov_b32_e32 v0, 0
	s_waitcnt vmcnt(0) expcnt(0) lgkmcnt(0)
	ds_read_b32 v2, v0
	ds_read_b32 v1, v0 offset:4
	s_waitcnt lgkmcnt(1)
	v_cmp_ne_u32_e32 vcc, 0, v2
	s_cbranch_vccnz .LBB0_398
	v_readlane_b32 s2, v251, 0
	s_mul_i32 s46, s91, s2
	s_add_u32 s2, s68, 0x1ef3d200
	s_addc_u32 s3, s69, 0
	s_add_u32 s4, s68, 0x1ef3d400
	s_addc_u32 s5, s69, 0
	s_add_u32 s6, s68, 0x1ef3d500
	s_addc_u32 s7, s69, 0
	s_add_u32 s10, s68, 0x1ef3d600
	s_addc_u32 s11, s69, 0
	s_add_u32 s12, s68, 0x1ef3d700
	s_addc_u32 s13, s69, 0
	s_add_u32 s14, s68, 0x1ef3d800
	s_addc_u32 s15, s69, 0
	s_add_u32 s16, s68, 0x1ef3d900
	s_addc_u32 s17, s69, 0
	s_add_u32 s18, s68, 0x1ef3da00
	s_addc_u32 s19, s69, 0
	s_add_u32 s20, s68, 0x1ef3db00
	s_addc_u32 s21, s69, 0
	s_add_u32 s22, s68, 0x1ef3dc00
	s_addc_u32 s23, s69, 0
	s_add_u32 s24, s68, 0x1ef3dd00
	s_addc_u32 s25, s69, 0
	s_add_u32 s26, s68, 0x1ef3de00
	s_addc_u32 s27, s69, 0
	s_add_u32 s28, s68, 0x1ef3df00
	s_addc_u32 s29, s69, 0
	s_add_u32 s30, s68, 0x1ef3e000
	s_addc_u32 s31, s69, 0
	s_add_u32 s34, s68, 0x1ef3e100
	s_addc_u32 s35, s69, 0
	s_add_u32 s36, s68, 0x1ef3e200
	s_addc_u32 s37, s69, 0
	s_add_u32 s38, s68, 0x1ef3e300
	s_mul_i32 s46, s46, s90
	s_addc_u32 s39, s69, 0
	s_mov_b32 s47, 1
	s_branch .LBB0_386
